# baseline (speedup 1.0000x reference)
; __device__ __forceinline__ int v_st(int k, int c) { const int kk = (k & ~0xC) | ((k & 4) << 1) | ((k & 8) >> 1); return ((kk >> 3) * 2 + (c >> 5)) * 512 + ((kk & 7) * 32 + (c & 31)) * 2; }
; __device__ __forceinline__ int v_rd_base(int lane) { return ((lane & 3) << 3) | (((lane >> 2) & 3) << 6) | (((lane >> 4) & 1) << 5) | (((lane >> 5) & 1) << 8); }
; #define SLOADP(i, Kp, Vp, t) do { const char* kp = (const char*)(Kp) + (long)(t) * (64 * 192); const char* vp = (const char*)(Vp) + (long)(t) * (64 * 128); \
;     sr_[i].k0 = *reinterpret_cast<const bf16x8*>(kp + kc0 * 16); sr_[i].k1 = *reinterpret_cast<const bf16x8*>(kp + kc1 * 16); \
;     sr_[i].v0 = *reinterpret_cast<const bf16x8*>(vp + tid * 16); } while (0)
; __device__ __forceinline__ void attn_phase(const bf16* __restrict__ qbase, const bf16* __restrict__ Kbase, const bf16* __restrict__ Vbase, bf16* __restrict__ mixbase) {
;     ...
;   int it = vtile(0); if (it >= nend) return;
;   char* lds = shm_raw;
;   const int tid = threadIdx.x, wid = tid >> 6, lane = tid & 63, r32 = lane & 31, hi = lane >> 5;
;   char* V_lds = lds + ATT_V0; char* K_lds = lds + ATT_K0;
;   float* wsf = (float*)(lds + ATT_WS) + wid * 64; float* al_l = wsf + 32;
;   const int kc0 = tid, kc1 = 512 + (tid & 255);
;   const int kst0 = (kc0 / 12) * KPITCH + (kc0 % 12) * 16, kst1 = (kc1 / 12) * KPITCH + (kc1 % 12) * 16;
;   const int vst = v_st(tid >> 3, (tid & 7) * 8);
;   const int vb0 = (int)(uintptr_t)V_lds + v_rd_base(lane);
;   const short one_ = (r32 == 0) ? (short)0x3F80 : (short)0; const bf16x8 ones = {one_, one_, one_, one_, one_, one_, one_, one_};
;   struct { bf16x8 k0, k1, v0; } sr_[2];
;   bf16x8 qr[6];
;   constexpr int SE = 0, SO = 1;
;     ...
;   const bf16 *Qw, *Kh, *Vh; bf16* Ob;
;   ITEM_PTRS(it, Qw, Kh, Vh, Ob);
;   #pragma unroll
;   for (int d0 = 0; d0 < 6; ++d0) qr[d0] = *reinterpret_cast<const bf16x8*>(Qw + d0 * 16);
;   SLOADP(SO, Kh, Vh, 0); SLOADP(SE, Kh, Vh, 1);
;   if (wid >= 4) __builtin_amdgcn_s_setprio(1);
.LBB0_505:
	s_or_b64 exec, exec, s[0:1]
	v_readlane_b32 s82, v254, 36
	v_readlane_b32 s84, v254, 39
	s_cmpk_lt_i32 s95, 0xc00
	v_readlane_b32 s83, v254, 37
	v_readlane_b32 s77, v254, 38
	v_readlane_b32 s85, v254, 40
	s_barrier
	s_cbranch_scc0 .LBB0_542
	s_movk_i32 s0, 0x200
	v_or_b32_sdwa v3, v252, s0 dst_sel:DWORD dst_unused:UNUSED_PAD src0_sel:BYTE_0 src1_sel:DWORD
	s_ashr_i32 s6, s95, 3
	s_ashr_i32 s0, s95, 6
	s_lshl_b32 s5, s95, 8
	v_and_b32_e32 v0, 31, v252
	v_lshrrev_b32_e32 v2, 1, v252
	s_and_b32 s4, s6, 7
	s_ashr_i32 s1, s0, 31
	s_mul_i32 s2, s0, 0x810
	s_and_b32 s5, s5, 0x700
	v_add_u32_e32 v4, 16, v0
	v_and_b32_e32 v2, 0x1e0, v2
	v_mov_b32_e32 v165, 0
	s_mul_hi_i32 s3, s0, 0x810
	s_add_u32 s2, s5, s2
	v_add_u32_e32 v162, v4, v2
	v_mov_b32_e32 v163, v165
	s_addc_u32 s3, 0, s3
	v_lshl_add_u64 v[4:5], s[2:3], 0, v[162:163]
	s_movk_i32 s8, 0x600
	v_mov_b64_e32 v[6:7], s[34:35]
	s_mov_b32 s40, 0
	v_mad_u64_u32 v[6:7], s[2:3], v4, s8, v[6:7]
	v_mad_i32_i24 v7, v5, s8, v7
	s_mul_i32 s2, s4, 0xc0
	s_mov_b32 s3, s40
	v_lshrrev_b32_e32 v1, 5, v193
	v_lshl_add_u64 v[168:169], v[6:7], 0, s[2:3]
	s_mul_hi_i32 s2, s6, 0x63000
	s_mul_i32 s3, s6, 0x63000
	s_mul_hi_i32 s9, s6, 0x42000
	s_mul_i32 s10, s6, 0x42000
	v_readlane_b32 s6, v254, 23
	v_lshlrev_b32_e32 v170, 4, v1
	v_mov_b32_e32 v171, v165
	v_readlane_b32 s7, v254, 24
	s_add_u32 s6, s6, s3
	v_lshl_add_u64 v[4:5], v[168:169], 0, v[170:171]
	s_addc_u32 s7, s7, s2
	global_load_dwordx4 v[80:83], v[4:5], off
	global_load_dwordx4 v[84:87], v[4:5], off offset:32
	global_load_dwordx4 v[88:91], v[4:5], off offset:64
	global_load_dwordx4 v[92:95], v[4:5], off offset:96
	global_load_dwordx4 v[96:99], v[4:5], off offset:128
	global_load_dwordx4 v[100:103], v[4:5], off offset:160
	s_add_u32 s60, s64, s10
	v_lshlrev_b32_e32 v160, 4, v252
	v_mov_b32_e32 v161, v165
	s_addc_u32 s61, s65, s9
	v_lshl_add_u64 v[4:5], s[60:61], 0, v[160:161]
	s_add_u32 s2, s6, 0x3000
	v_lshlrev_b32_e32 v166, 4, v3
	s_addc_u32 s3, s7, 0
	v_add_co_u32_e32 v4, vcc, 0x2000, v4
	global_load_dwordx4 v[132:135], v160, s[6:7]
	global_load_dwordx4 v[136:139], v160, s[60:61]
	global_load_dwordx4 v[140:143], v166, s[6:7]
	global_load_dwordx4 v[104:107], v160, s[2:3]
	v_addc_co_u32_e32 v5, vcc, 0, v5, vcc
	global_load_dwordx4 v[108:111], v166, s[2:3]
	global_load_dwordx4 v[112:115], v[4:5], off
	s_movk_i32 s2, 0xff
	v_lshlrev_b32_e32 v4, 3, v1
	v_cmp_lt_u32_e32 vcc, s2, v252
	s_and_saveexec_b64 s[2:3], vcc
	s_cbranch_execz .Latt_prio_done
	s_setprio 1
.Latt_prio_done:
	s_or_b64 exec, exec, s[2:3]
	s_lshl_b64 s[0:1], s[0:1], 22
	s_add_u32 s0, s58, s0
	s_addc_u32 s1, s59, s1
	s_lshl_b32 s2, s5, 11
	s_add_u32 s0, s0, s2
	v_lshrrev_b32_e32 v7, 3, v252
	v_lshrrev_b32_e32 v8, 2, v252
	s_addc_u32 s1, s1, 0
	s_lshl_b32 s2, s4, 7
	v_and_b32_e32 v7, 0x70, v7
	v_and_b32_e32 v8, 8, v8
	v_and_b32_e32 v10, 4, v252
	s_add_u32 s0, s0, s2
	v_lshrrev_b32_e32 v9, 4, v252
	v_or3_b32 v7, v7, v8, v10
	v_bfe_u32 v8, v252, 3, 2
	s_addc_u32 s1, s1, 0
	v_and_or_b32 v8, v9, 4, v8
	v_and_b32_e32 v9, 48, v160
	s_add_u32 s72, s0, 0x400
	v_lshl_or_b32 v8, v8, 6, v9
	v_lshlrev_b32_e32 v9, 3, v252
	v_lshlrev_b32_e32 v11, 1, v252
	s_addc_u32 s73, s1, 0
	v_and_b32_e32 v5, 0x3c0, v252
	v_mul_u32_u24_e32 v6, 0x1556, v3
	v_and_b32_e32 v10, 0xc0, v160
	v_and_b32_e32 v11, 32, v11
	v_and_b32_e32 v9, 0x118, v9
	v_lshl_add_u32 v171, v5, 2, 0
	v_mul_u32_u24_e32 v5, 0x1556, v252
	v_lshrrev_b32_e32 v6, 16, v6
	v_or3_b32 v9, v11, v10, v9
	v_mov_b32_e32 v10, 0x3f80
	v_and_b32_e32 v116, 15, v252
	v_bfe_u32 v117, v252, 4, 1
	v_cmp_eq_u32_e32 vcc, v116, v117
	s_cmp_lg_u32 0, -1
	s_movk_i32 s1, 0xd0
	v_lshlrev_b32_e32 v174, 13, v1
	v_mov_b32_e32 v1, 4
	v_lshrrev_b32_e32 v5, 16, v5
	v_cndmask_b32_e32 v10, 0, v10, vcc
	v_add_lshl_u32 v3, v3, v6, 4
	v_lshl_or_b32 v6, v7, 7, v8
	s_cselect_b32 s0, 0, 0
	v_mad_u32_u24 v7, v0, s1, 0
	s_mov_b32 s1, 0x5040100
	v_and_b32_e32 v8, 32, v252
	v_lshlrev_b32_sdwa v178, v1, v252 dst_sel:DWORD dst_unused:UNUSED_PAD src0_sel:DWORD src1_sel:BYTE_0
	v_mbcnt_hi_u32_b32 v1, -1, v210
	v_add_lshl_u32 v5, v252, v5, 4
	v_add_u32_e32 v212, s0, v9
	v_perm_b32 v116, v10, v10, s1
	s_addk_i32 s0, 0x2000
	v_and_or_b32 v1, v1, 64, v8
	v_mov_b32_e32 v167, v165
	v_mov_b32_e32 v117, v116
	v_mov_b32_e32 v118, v116
	v_mov_b32_e32 v119, v116
	v_cmp_gt_u32_e64 s[4:5], 32, v193
	v_lshl_add_u32 v213, v0, 2, v171
	v_add_u32_e32 v214, s0, v9
	v_lshlrev_b32_e32 v172, 11, v2
	v_mov_b32_e32 v173, v165
	v_mov_b32_e32 v175, v165
	s_mov_b32 s3, 0x8000
	v_or_b32_e32 v176, 0x8000, v160
	v_mov_b32_e32 v177, v161
	v_mov_b32_e32 v179, v165
	s_mov_b32 s9, 0x429cc470
	s_mov_b32 s2, 0x3e16c740
	s_movk_i32 s12, 0x4000
	s_mov_b64 s[10:11], 0x2000
	s_mov_b32 s13, 0x9000
	s_mov_b32 s16, 0xc000
	s_mov_b64 s[14:15], 0x4000
	v_lshlrev_b32_e32 v215, 2, v1
	v_lshlrev_b32_e32 v180, 1, v0
	s_movk_i32 s17, 0x1000
	s_movk_i32 s33, 0x5000
	s_mov_b32 s62, 0xd000
	v_add_u32_e32 v216, 0, v6
	v_add_u32_e32 v217, 0, v5
	v_add_u32_e32 v218, 0, v3
	v_add_u32_e32 v219, v7, v170
	v_mov_b32_e32 v220, 0xf149f2ca
	v_lshlrev_b32_e32 v164, 1, v4
	s_mov_b32 s63, 0
	s_mov_b64 s[68:69], s[72:73]
	s_mov_b64 s[30:31], s[60:61]
	s_mov_b64 s[28:29], s[6:7]
	v_bfe_u32 v251, v252, 4, 2
	v_lshlrev_b32_e32 v251, 4, v251
	v_and_b32_e32 v48, 1, v252
	v_lshl_or_b32 v251, v48, 6, v251
	v_add_u32_e32 v251, v251, v171
	s_waitcnt vmcnt(0)
	s_branch .LBB0_510
